# v014 + merge-phase and FFN2-down epilogues: all residual/gate loads issued up front with counted vmcnt waits instead of 16 serialized load-wait round trips
# speedup vs baseline: 1.0087x; 1.0087x over previous
; DI float bf_lo(unsigned u) { return __uint_as_float(u << 16); }
; DI float bf_hi(unsigned u) { return __uint_as_float(u & 0xffff0000u); }
;     DI void operator()(Acc& acc, const pg8::Unit& u, int wr, int wc, int fr, int fq, const Pre&) const {
;         const int col = u.pn * 256 + wc * 32 + fq * 8;
; #pragma unroll
;         for (int ai = 0; ai < 2; ++ai)
; #pragma unroll
;             for (int m = 0; m < 4; ++m) {
;                 const int row = u.pm * 256 + ai * 128 + wr * 64 + m * 16 + fr;
; #pragma unroll
;                 for (int bj = 0; bj < 2; ++bj) {
;                     const u32x4 gq = *(const u32x4*)(MG + (size_t)row * 2048 + (u.src ? 1024 : 0) + col + bj * 128);
;                     const float c[8] = {bf_lo(gq.x), bf_hi(gq.x), bf_lo(gq.y), bf_hi(gq.y), bf_lo(gq.z), bf_hi(gq.z), bf_lo(gq.w), bf_hi(gq.w)};
;                     if (u.src == 0) {
; #pragma unroll
;                         for (int e = 0; e < 8; ++e) acc[ai][bj][m][e >> 2][e & 3] *= c[e];
.LBB0_975:
	s_lshl_b32 s37, s6, 8
	v_add_u32_e32 v148, s37, v1
	v_lshl_or_b32 v146, s10, 8, v166
	s_cmp_eq_u32 s7, 0
	s_cselect_b32 s10, 0, 0x800
	s_cselect_b64 s[6:7], -1, 0
	v_lshlrev_b32_e32 v149, 12, v148
	v_lshl_add_u32 v150, v146, 1, s10
	v_add_u32_e32 v152, v149, v150
	v_add_u32_e32 v153, 0x10000, v152
	v_add_u32_e32 v154, 0x20000, v152
	v_add_u32_e32 v155, 0x30000, v152
	v_add_u32_e32 v156, 0x80000, v152
	v_add_u32_e32 v157, 0x90000, v152
	v_add_u32_e32 v158, 0xa0000, v152
	v_add_u32_e32 v159, 0xb0000, v152
	global_load_dwordx4 v[188:191], v152, s[16:17]
	global_load_dwordx4 v[192:195], v152, s[16:17] offset:256
	global_load_dwordx4 v[196:199], v153, s[16:17]
	global_load_dwordx4 v[200:203], v153, s[16:17] offset:256
	global_load_dwordx4 v[204:207], v154, s[16:17]
	global_load_dwordx4 v[208:211], v154, s[16:17] offset:256
	global_load_dwordx4 v[212:215], v155, s[16:17]
	global_load_dwordx4 v[216:219], v155, s[16:17] offset:256
	global_load_dwordx4 v[220:223], v156, s[16:17]
	global_load_dwordx4 v[224:227], v156, s[16:17] offset:256
	global_load_dwordx4 v[228:231], v157, s[16:17]
	global_load_dwordx4 v[232:235], v157, s[16:17] offset:256
	global_load_dwordx4 v[236:239], v158, s[16:17]
	global_load_dwordx4 v[240:243], v158, s[16:17] offset:256
	global_load_dwordx4 v[244:247], v159, s[16:17]
	global_load_dwordx4 v[248:251], v159, s[16:17] offset:256
	s_and_b64 vcc, exec, s[6:7]
	s_cbranch_vccz .Lmrg_src1
	s_waitcnt vmcnt(15)
	v_lshlrev_b32_e32 v168, 16, v188
	v_and_b32_e32 v169, 0xffff0000, v188
	v_lshlrev_b32_e32 v170, 16, v189
	v_and_b32_e32 v171, 0xffff0000, v189
	v_lshlrev_b32_e32 v172, 16, v190
	v_and_b32_e32 v173, 0xffff0000, v190
	v_lshlrev_b32_e32 v174, 16, v191
	v_and_b32_e32 v175, 0xffff0000, v191
	v_pk_mul_f32 v[126:127], v[126:127], v[168:169]
	v_pk_mul_f32 v[128:129], v[128:129], v[170:171]
	v_pk_mul_f32 v[122:123], v[122:123], v[172:173]
	v_pk_mul_f32 v[124:125], v[124:125], v[174:175]
	s_waitcnt vmcnt(14)
	v_lshlrev_b32_e32 v168, 16, v192
	v_and_b32_e32 v169, 0xffff0000, v192
	v_lshlrev_b32_e32 v170, 16, v193
	v_and_b32_e32 v171, 0xffff0000, v193
	v_lshlrev_b32_e32 v172, 16, v194
	v_and_b32_e32 v173, 0xffff0000, v194
	v_lshlrev_b32_e32 v174, 16, v195
	v_and_b32_e32 v175, 0xffff0000, v195
	v_pk_mul_f32 v[94:95], v[94:95], v[168:169]
	v_pk_mul_f32 v[96:97], v[96:97], v[170:171]
	v_pk_mul_f32 v[90:91], v[90:91], v[172:173]
	v_pk_mul_f32 v[92:93], v[92:93], v[174:175]
	s_waitcnt vmcnt(13)
	v_lshlrev_b32_e32 v168, 16, v196
	v_and_b32_e32 v169, 0xffff0000, v196
	v_lshlrev_b32_e32 v170, 16, v197
	v_and_b32_e32 v171, 0xffff0000, v197
	v_lshlrev_b32_e32 v172, 16, v198
	v_and_b32_e32 v173, 0xffff0000, v198
	v_lshlrev_b32_e32 v174, 16, v199
	v_and_b32_e32 v175, 0xffff0000, v199
	v_pk_mul_f32 v[118:119], v[118:119], v[168:169]
	v_pk_mul_f32 v[120:121], v[120:121], v[170:171]
	v_pk_mul_f32 v[114:115], v[114:115], v[172:173]
	v_pk_mul_f32 v[116:117], v[116:117], v[174:175]
	s_waitcnt vmcnt(12)
	v_lshlrev_b32_e32 v168, 16, v200
	v_and_b32_e32 v169, 0xffff0000, v200
	v_lshlrev_b32_e32 v170, 16, v201
	v_and_b32_e32 v171, 0xffff0000, v201
	v_lshlrev_b32_e32 v172, 16, v202
	v_and_b32_e32 v173, 0xffff0000, v202
	v_lshlrev_b32_e32 v174, 16, v203
	v_and_b32_e32 v175, 0xffff0000, v203
	v_pk_mul_f32 v[86:87], v[86:87], v[168:169]
	v_pk_mul_f32 v[88:89], v[88:89], v[170:171]
	v_pk_mul_f32 v[82:83], v[82:83], v[172:173]
	v_pk_mul_f32 v[84:85], v[84:85], v[174:175]
	s_waitcnt vmcnt(11)
	v_lshlrev_b32_e32 v168, 16, v204
	v_and_b32_e32 v169, 0xffff0000, v204
	v_lshlrev_b32_e32 v170, 16, v205
	v_and_b32_e32 v171, 0xffff0000, v205
	v_lshlrev_b32_e32 v172, 16, v206
	v_and_b32_e32 v173, 0xffff0000, v206
	v_lshlrev_b32_e32 v174, 16, v207
	v_and_b32_e32 v175, 0xffff0000, v207
	v_pk_mul_f32 v[110:111], v[110:111], v[168:169]
	v_pk_mul_f32 v[112:113], v[112:113], v[170:171]
	v_pk_mul_f32 v[106:107], v[106:107], v[172:173]
	v_pk_mul_f32 v[108:109], v[108:109], v[174:175]
	s_waitcnt vmcnt(10)
	v_lshlrev_b32_e32 v168, 16, v208
	v_and_b32_e32 v169, 0xffff0000, v208
	v_lshlrev_b32_e32 v170, 16, v209
	v_and_b32_e32 v171, 0xffff0000, v209
	v_lshlrev_b32_e32 v172, 16, v210
	v_and_b32_e32 v173, 0xffff0000, v210
	v_lshlrev_b32_e32 v174, 16, v211
	v_and_b32_e32 v175, 0xffff0000, v211
	v_pk_mul_f32 v[78:79], v[78:79], v[168:169]
	v_pk_mul_f32 v[80:81], v[80:81], v[170:171]
	v_pk_mul_f32 v[74:75], v[74:75], v[172:173]
	v_pk_mul_f32 v[76:77], v[76:77], v[174:175]
	s_waitcnt vmcnt(9)
	v_lshlrev_b32_e32 v168, 16, v212
	v_and_b32_e32 v169, 0xffff0000, v212
	v_lshlrev_b32_e32 v170, 16, v213
	v_and_b32_e32 v171, 0xffff0000, v213
	v_lshlrev_b32_e32 v172, 16, v214
	v_and_b32_e32 v173, 0xffff0000, v214
	v_lshlrev_b32_e32 v174, 16, v215
	v_and_b32_e32 v175, 0xffff0000, v215
	v_pk_mul_f32 v[102:103], v[102:103], v[168:169]
	v_pk_mul_f32 v[104:105], v[104:105], v[170:171]
	v_pk_mul_f32 v[98:99], v[98:99], v[172:173]
	v_pk_mul_f32 v[100:101], v[100:101], v[174:175]
	s_waitcnt vmcnt(8)
	v_lshlrev_b32_e32 v168, 16, v216
	v_and_b32_e32 v169, 0xffff0000, v216
	v_lshlrev_b32_e32 v170, 16, v217
	v_and_b32_e32 v171, 0xffff0000, v217
	v_lshlrev_b32_e32 v172, 16, v218
	v_and_b32_e32 v173, 0xffff0000, v218
	v_lshlrev_b32_e32 v174, 16, v219
	v_and_b32_e32 v175, 0xffff0000, v219
	v_pk_mul_f32 v[70:71], v[70:71], v[168:169]
	v_pk_mul_f32 v[72:73], v[72:73], v[170:171]
	v_pk_mul_f32 v[66:67], v[66:67], v[172:173]
	v_pk_mul_f32 v[68:69], v[68:69], v[174:175]
	s_waitcnt vmcnt(7)
; DI float bf_lo(unsigned u) { return __uint_as_float(u << 16); }
; DI float bf_hi(unsigned u) { return __uint_as_float(u & 0xffff0000u); }
;     DI void operator()(Acc& acc, const pg8::Unit& u, int wr, int wc, int fr, int fq, const Pre&) const {
;     ...
;                 for (int bj = 0; bj < 2; ++bj) {
;                     const u32x4 gq = *(const u32x4*)(MG + (size_t)row * 2048 + (u.src ? 1024 : 0) + col + bj * 128);
;                     const float c[8] = {bf_lo(gq.x), bf_hi(gq.x), bf_lo(gq.y), bf_hi(gq.y), bf_lo(gq.z), bf_hi(gq.z), bf_lo(gq.w), bf_hi(gq.w)};
;                     if (u.src == 0) {
; #pragma unroll
;                         for (int e = 0; e < 8; ++e) acc[ai][bj][m][e >> 2][e & 3] *= c[e];
;                     } else {
;                         f32x4 v0, v1;
; #pragma unroll
;                         for (int i = 0; i < 4; ++i) { v0[i] = acc[ai][bj][m][0][i] * c[i]; v1[i] = acc[ai][bj][m][1][i] * c[4 + i]; }
;                         store8(OUT + (size_t)row * DM + col + bj * 128, v0, v1);
	v_lshlrev_b32_e32 v168, 16, v220
	v_and_b32_e32 v169, 0xffff0000, v220
	v_lshlrev_b32_e32 v170, 16, v221
	v_and_b32_e32 v171, 0xffff0000, v221
	v_lshlrev_b32_e32 v172, 16, v222
	v_and_b32_e32 v173, 0xffff0000, v222
	v_lshlrev_b32_e32 v174, 16, v223
	v_and_b32_e32 v175, 0xffff0000, v223
	v_pk_mul_f32 v[62:63], v[62:63], v[168:169]
	v_pk_mul_f32 v[64:65], v[64:65], v[170:171]
	v_pk_mul_f32 v[58:59], v[58:59], v[172:173]
	v_pk_mul_f32 v[60:61], v[60:61], v[174:175]
	s_waitcnt vmcnt(6)
	v_lshlrev_b32_e32 v168, 16, v224
	v_and_b32_e32 v169, 0xffff0000, v224
	v_lshlrev_b32_e32 v170, 16, v225
	v_and_b32_e32 v171, 0xffff0000, v225
	v_lshlrev_b32_e32 v172, 16, v226
	v_and_b32_e32 v173, 0xffff0000, v226
	v_lshlrev_b32_e32 v174, 16, v227
	v_and_b32_e32 v175, 0xffff0000, v227
	v_pk_mul_f32 v[30:31], v[30:31], v[168:169]
	v_pk_mul_f32 v[32:33], v[32:33], v[170:171]
	v_pk_mul_f32 v[26:27], v[26:27], v[172:173]
	v_pk_mul_f32 v[28:29], v[28:29], v[174:175]
	s_waitcnt vmcnt(5)
	v_lshlrev_b32_e32 v168, 16, v228
	v_and_b32_e32 v169, 0xffff0000, v228
	v_lshlrev_b32_e32 v170, 16, v229
	v_and_b32_e32 v171, 0xffff0000, v229
	v_lshlrev_b32_e32 v172, 16, v230
	v_and_b32_e32 v173, 0xffff0000, v230
	v_lshlrev_b32_e32 v174, 16, v231
	v_and_b32_e32 v175, 0xffff0000, v231
	v_pk_mul_f32 v[54:55], v[54:55], v[168:169]
	v_pk_mul_f32 v[56:57], v[56:57], v[170:171]
	v_pk_mul_f32 v[50:51], v[50:51], v[172:173]
	v_pk_mul_f32 v[52:53], v[52:53], v[174:175]
	s_waitcnt vmcnt(4)
	v_lshlrev_b32_e32 v168, 16, v232
	v_and_b32_e32 v169, 0xffff0000, v232
	v_lshlrev_b32_e32 v170, 16, v233
	v_and_b32_e32 v171, 0xffff0000, v233
	v_lshlrev_b32_e32 v172, 16, v234
	v_and_b32_e32 v173, 0xffff0000, v234
	v_lshlrev_b32_e32 v174, 16, v235
	v_and_b32_e32 v175, 0xffff0000, v235
	v_pk_mul_f32 v[22:23], v[22:23], v[168:169]
	v_pk_mul_f32 v[24:25], v[24:25], v[170:171]
	v_pk_mul_f32 v[18:19], v[18:19], v[172:173]
	v_pk_mul_f32 v[20:21], v[20:21], v[174:175]
	s_waitcnt vmcnt(3)
	v_lshlrev_b32_e32 v168, 16, v236
	v_and_b32_e32 v169, 0xffff0000, v236
	v_lshlrev_b32_e32 v170, 16, v237
	v_and_b32_e32 v171, 0xffff0000, v237
	v_lshlrev_b32_e32 v172, 16, v238
	v_and_b32_e32 v173, 0xffff0000, v238
	v_lshlrev_b32_e32 v174, 16, v239
	v_and_b32_e32 v175, 0xffff0000, v239
	v_pk_mul_f32 v[46:47], v[46:47], v[168:169]
	v_pk_mul_f32 v[48:49], v[48:49], v[170:171]
	v_pk_mul_f32 v[42:43], v[42:43], v[172:173]
	v_pk_mul_f32 v[44:45], v[44:45], v[174:175]
	s_waitcnt vmcnt(2)
	v_lshlrev_b32_e32 v168, 16, v240
	v_and_b32_e32 v169, 0xffff0000, v240
	v_lshlrev_b32_e32 v170, 16, v241
	v_and_b32_e32 v171, 0xffff0000, v241
	v_lshlrev_b32_e32 v172, 16, v242
	v_and_b32_e32 v173, 0xffff0000, v242
	v_lshlrev_b32_e32 v174, 16, v243
	v_and_b32_e32 v175, 0xffff0000, v243
	v_pk_mul_f32 v[14:15], v[14:15], v[168:169]
	v_pk_mul_f32 v[16:17], v[16:17], v[170:171]
	v_pk_mul_f32 v[10:11], v[10:11], v[172:173]
	v_pk_mul_f32 v[12:13], v[12:13], v[174:175]
	s_waitcnt vmcnt(1)
	v_lshlrev_b32_e32 v168, 16, v244
	v_and_b32_e32 v169, 0xffff0000, v244
	v_lshlrev_b32_e32 v170, 16, v245
	v_and_b32_e32 v171, 0xffff0000, v245
	v_lshlrev_b32_e32 v172, 16, v246
	v_and_b32_e32 v173, 0xffff0000, v246
	v_lshlrev_b32_e32 v174, 16, v247
	v_and_b32_e32 v175, 0xffff0000, v247
	v_pk_mul_f32 v[38:39], v[38:39], v[168:169]
	v_pk_mul_f32 v[40:41], v[40:41], v[170:171]
	v_pk_mul_f32 v[34:35], v[34:35], v[172:173]
	v_pk_mul_f32 v[36:37], v[36:37], v[174:175]
	s_waitcnt vmcnt(0)
	v_lshlrev_b32_e32 v168, 16, v248
	v_and_b32_e32 v169, 0xffff0000, v248
	v_lshlrev_b32_e32 v170, 16, v249
	v_and_b32_e32 v171, 0xffff0000, v249
	v_lshlrev_b32_e32 v172, 16, v250
	v_and_b32_e32 v173, 0xffff0000, v250
	v_lshlrev_b32_e32 v174, 16, v251
	v_and_b32_e32 v175, 0xffff0000, v251
	v_pk_mul_f32 v[6:7], v[6:7], v[168:169]
	v_pk_mul_f32 v[8:9], v[8:9], v[170:171]
	v_pk_mul_f32 v[2:3], v[2:3], v[172:173]
	v_pk_mul_f32 v[4:5], v[4:5], v[174:175]
	s_branch .Lmrg_done
.Lmrg_src1:
	v_lshlrev_b32_e32 v149, 11, v148
	v_lshl_add_u32 v160, v146, 1, v149
	v_mov_b32_e32 v152, v160
	v_add_u32_e32 v153, 0x8000, v160
	v_add_u32_e32 v154, 0x10000, v160
	v_add_u32_e32 v155, 0x18000, v160
	v_add_u32_e32 v156, 0x40000, v160
	v_add_u32_e32 v157, 0x48000, v160
	v_add_u32_e32 v158, 0x50000, v160
	v_add_u32_e32 v159, 0x58000, v160
	s_waitcnt vmcnt(15)
	v_lshlrev_b32_e32 v168, 16, v188
	v_and_b32_e32 v169, 0xffff0000, v188
	v_lshlrev_b32_e32 v170, 16, v189
	v_and_b32_e32 v171, 0xffff0000, v189
	v_lshlrev_b32_e32 v172, 16, v190
	v_and_b32_e32 v173, 0xffff0000, v190
	v_lshlrev_b32_e32 v174, 16, v191
	v_and_b32_e32 v175, 0xffff0000, v191
	v_pk_mul_f32 v[176:177], v[126:127], v[168:169]
	v_pk_mul_f32 v[178:179], v[128:129], v[170:171]
	v_pk_mul_f32 v[180:181], v[122:123], v[172:173]
	v_pk_mul_f32 v[182:183], v[124:125], v[174:175]
	v_cvt_pk_bf16_f32 v176, v176, v177
	v_cvt_pk_bf16_f32 v177, v178, v179
	v_cvt_pk_bf16_f32 v178, v180, v181
	v_cvt_pk_bf16_f32 v179, v182, v183
	global_store_dwordx4 v152, v[176:179], s[18:19]
	s_nop 1
	s_waitcnt vmcnt(15)
	v_lshlrev_b32_e32 v168, 16, v192
	v_and_b32_e32 v169, 0xffff0000, v192
	v_lshlrev_b32_e32 v170, 16, v193
	v_and_b32_e32 v171, 0xffff0000, v193
	v_lshlrev_b32_e32 v172, 16, v194
	v_and_b32_e32 v173, 0xffff0000, v194
	v_lshlrev_b32_e32 v174, 16, v195
	v_and_b32_e32 v175, 0xffff0000, v195
	v_pk_mul_f32 v[176:177], v[94:95], v[168:169]
	v_pk_mul_f32 v[178:179], v[96:97], v[170:171]
	v_pk_mul_f32 v[180:181], v[90:91], v[172:173]
	v_pk_mul_f32 v[182:183], v[92:93], v[174:175]
	v_cvt_pk_bf16_f32 v176, v176, v177
	v_cvt_pk_bf16_f32 v177, v178, v179
	v_cvt_pk_bf16_f32 v178, v180, v181
	v_cvt_pk_bf16_f32 v179, v182, v183
	global_store_dwordx4 v152, v[176:179], s[18:19] offset:256
	s_nop 1
	s_waitcnt vmcnt(15)
; DI float bf_lo(unsigned u) { return __uint_as_float(u << 16); }
; DI float bf_hi(unsigned u) { return __uint_as_float(u & 0xffff0000u); }
;     DI void operator()(Acc& acc, const pg8::Unit& u, int wr, int wc, int fr, int fq, const Pre&) const {
;     ...
;                 for (int bj = 0; bj < 2; ++bj) {
;                     const u32x4 gq = *(const u32x4*)(MG + (size_t)row * 2048 + (u.src ? 1024 : 0) + col + bj * 128);
;                     const float c[8] = {bf_lo(gq.x), bf_hi(gq.x), bf_lo(gq.y), bf_hi(gq.y), bf_lo(gq.z), bf_hi(gq.z), bf_lo(gq.w), bf_hi(gq.w)};
;                     if (u.src == 0) {
; #pragma unroll
;                         for (int e = 0; e < 8; ++e) acc[ai][bj][m][e >> 2][e & 3] *= c[e];
;                     } else {
;                         f32x4 v0, v1;
; #pragma unroll
;                         for (int i = 0; i < 4; ++i) { v0[i] = acc[ai][bj][m][0][i] * c[i]; v1[i] = acc[ai][bj][m][1][i] * c[4 + i]; }
;                         store8(OUT + (size_t)row * DM + col + bj * 128, v0, v1);
	v_lshlrev_b32_e32 v168, 16, v196
	v_and_b32_e32 v169, 0xffff0000, v196
	v_lshlrev_b32_e32 v170, 16, v197
	v_and_b32_e32 v171, 0xffff0000, v197
	v_lshlrev_b32_e32 v172, 16, v198
	v_and_b32_e32 v173, 0xffff0000, v198
	v_lshlrev_b32_e32 v174, 16, v199
	v_and_b32_e32 v175, 0xffff0000, v199
	v_pk_mul_f32 v[176:177], v[118:119], v[168:169]
	v_pk_mul_f32 v[178:179], v[120:121], v[170:171]
	v_pk_mul_f32 v[180:181], v[114:115], v[172:173]
	v_pk_mul_f32 v[182:183], v[116:117], v[174:175]
	v_cvt_pk_bf16_f32 v176, v176, v177
	v_cvt_pk_bf16_f32 v177, v178, v179
	v_cvt_pk_bf16_f32 v178, v180, v181
	v_cvt_pk_bf16_f32 v179, v182, v183
	global_store_dwordx4 v153, v[176:179], s[18:19]
	s_nop 1
	s_waitcnt vmcnt(15)
	v_lshlrev_b32_e32 v168, 16, v200
	v_and_b32_e32 v169, 0xffff0000, v200
	v_lshlrev_b32_e32 v170, 16, v201
	v_and_b32_e32 v171, 0xffff0000, v201
	v_lshlrev_b32_e32 v172, 16, v202
	v_and_b32_e32 v173, 0xffff0000, v202
	v_lshlrev_b32_e32 v174, 16, v203
	v_and_b32_e32 v175, 0xffff0000, v203
	v_pk_mul_f32 v[176:177], v[86:87], v[168:169]
	v_pk_mul_f32 v[178:179], v[88:89], v[170:171]
	v_pk_mul_f32 v[180:181], v[82:83], v[172:173]
	v_pk_mul_f32 v[182:183], v[84:85], v[174:175]
	v_cvt_pk_bf16_f32 v176, v176, v177
	v_cvt_pk_bf16_f32 v177, v178, v179
	v_cvt_pk_bf16_f32 v178, v180, v181
	v_cvt_pk_bf16_f32 v179, v182, v183
	global_store_dwordx4 v153, v[176:179], s[18:19] offset:256
	s_nop 1
	s_waitcnt vmcnt(15)
	v_lshlrev_b32_e32 v168, 16, v204
	v_and_b32_e32 v169, 0xffff0000, v204
	v_lshlrev_b32_e32 v170, 16, v205
	v_and_b32_e32 v171, 0xffff0000, v205
	v_lshlrev_b32_e32 v172, 16, v206
	v_and_b32_e32 v173, 0xffff0000, v206
	v_lshlrev_b32_e32 v174, 16, v207
	v_and_b32_e32 v175, 0xffff0000, v207
	v_pk_mul_f32 v[176:177], v[110:111], v[168:169]
	v_pk_mul_f32 v[178:179], v[112:113], v[170:171]
	v_pk_mul_f32 v[180:181], v[106:107], v[172:173]
	v_pk_mul_f32 v[182:183], v[108:109], v[174:175]
	v_cvt_pk_bf16_f32 v176, v176, v177
	v_cvt_pk_bf16_f32 v177, v178, v179
	v_cvt_pk_bf16_f32 v178, v180, v181
	v_cvt_pk_bf16_f32 v179, v182, v183
	global_store_dwordx4 v154, v[176:179], s[18:19]
	s_nop 1
	s_waitcnt vmcnt(15)
	v_lshlrev_b32_e32 v168, 16, v208
	v_and_b32_e32 v169, 0xffff0000, v208
	v_lshlrev_b32_e32 v170, 16, v209
	v_and_b32_e32 v171, 0xffff0000, v209
	v_lshlrev_b32_e32 v172, 16, v210
	v_and_b32_e32 v173, 0xffff0000, v210
	v_lshlrev_b32_e32 v174, 16, v211
	v_and_b32_e32 v175, 0xffff0000, v211
	v_pk_mul_f32 v[176:177], v[78:79], v[168:169]
	v_pk_mul_f32 v[178:179], v[80:81], v[170:171]
	v_pk_mul_f32 v[180:181], v[74:75], v[172:173]
	v_pk_mul_f32 v[182:183], v[76:77], v[174:175]
	v_cvt_pk_bf16_f32 v176, v176, v177
	v_cvt_pk_bf16_f32 v177, v178, v179
	v_cvt_pk_bf16_f32 v178, v180, v181
	v_cvt_pk_bf16_f32 v179, v182, v183
	global_store_dwordx4 v154, v[176:179], s[18:19] offset:256
	s_nop 1
	s_waitcnt vmcnt(15)
	v_lshlrev_b32_e32 v168, 16, v212
	v_and_b32_e32 v169, 0xffff0000, v212
	v_lshlrev_b32_e32 v170, 16, v213
	v_and_b32_e32 v171, 0xffff0000, v213
	v_lshlrev_b32_e32 v172, 16, v214
	v_and_b32_e32 v173, 0xffff0000, v214
	v_lshlrev_b32_e32 v174, 16, v215
	v_and_b32_e32 v175, 0xffff0000, v215
	v_pk_mul_f32 v[176:177], v[102:103], v[168:169]
	v_pk_mul_f32 v[178:179], v[104:105], v[170:171]
	v_pk_mul_f32 v[180:181], v[98:99], v[172:173]
	v_pk_mul_f32 v[182:183], v[100:101], v[174:175]
	v_cvt_pk_bf16_f32 v176, v176, v177
	v_cvt_pk_bf16_f32 v177, v178, v179
	v_cvt_pk_bf16_f32 v178, v180, v181
	v_cvt_pk_bf16_f32 v179, v182, v183
	global_store_dwordx4 v155, v[176:179], s[18:19]
	s_nop 1
	s_waitcnt vmcnt(15)
	v_lshlrev_b32_e32 v168, 16, v216
	v_and_b32_e32 v169, 0xffff0000, v216
	v_lshlrev_b32_e32 v170, 16, v217
	v_and_b32_e32 v171, 0xffff0000, v217
	v_lshlrev_b32_e32 v172, 16, v218
	v_and_b32_e32 v173, 0xffff0000, v218
	v_lshlrev_b32_e32 v174, 16, v219
	v_and_b32_e32 v175, 0xffff0000, v219
	v_pk_mul_f32 v[176:177], v[70:71], v[168:169]
	v_pk_mul_f32 v[178:179], v[72:73], v[170:171]
	v_pk_mul_f32 v[180:181], v[66:67], v[172:173]
	v_pk_mul_f32 v[182:183], v[68:69], v[174:175]
	v_cvt_pk_bf16_f32 v176, v176, v177
	v_cvt_pk_bf16_f32 v177, v178, v179
	v_cvt_pk_bf16_f32 v178, v180, v181
	v_cvt_pk_bf16_f32 v179, v182, v183
	global_store_dwordx4 v155, v[176:179], s[18:19] offset:256
	s_nop 1
	s_waitcnt vmcnt(15)
	v_lshlrev_b32_e32 v168, 16, v220
	v_and_b32_e32 v169, 0xffff0000, v220
	v_lshlrev_b32_e32 v170, 16, v221
	v_and_b32_e32 v171, 0xffff0000, v221
	v_lshlrev_b32_e32 v172, 16, v222
	v_and_b32_e32 v173, 0xffff0000, v222
	v_lshlrev_b32_e32 v174, 16, v223
	v_and_b32_e32 v175, 0xffff0000, v223
	v_pk_mul_f32 v[176:177], v[62:63], v[168:169]
	v_pk_mul_f32 v[178:179], v[64:65], v[170:171]
	v_pk_mul_f32 v[180:181], v[58:59], v[172:173]
	v_pk_mul_f32 v[182:183], v[60:61], v[174:175]
	v_cvt_pk_bf16_f32 v176, v176, v177
	v_cvt_pk_bf16_f32 v177, v178, v179
	v_cvt_pk_bf16_f32 v178, v180, v181
	v_cvt_pk_bf16_f32 v179, v182, v183
	global_store_dwordx4 v156, v[176:179], s[18:19]
	s_nop 1
	s_waitcnt vmcnt(15)
; DI float bf_lo(unsigned u) { return __uint_as_float(u << 16); }
; DI float bf_hi(unsigned u) { return __uint_as_float(u & 0xffff0000u); }
;     DI void operator()(Acc& acc, const pg8::Unit& u, int wr, int wc, int fr, int fq, const Pre&) const {
;     ...
;                 for (int bj = 0; bj < 2; ++bj) {
;                     const u32x4 gq = *(const u32x4*)(MG + (size_t)row * 2048 + (u.src ? 1024 : 0) + col + bj * 128);
;                     const float c[8] = {bf_lo(gq.x), bf_hi(gq.x), bf_lo(gq.y), bf_hi(gq.y), bf_lo(gq.z), bf_hi(gq.z), bf_lo(gq.w), bf_hi(gq.w)};
;                     if (u.src == 0) {
; #pragma unroll
;                         for (int e = 0; e < 8; ++e) acc[ai][bj][m][e >> 2][e & 3] *= c[e];
;                     } else {
;                         f32x4 v0, v1;
; #pragma unroll
;                         for (int i = 0; i < 4; ++i) { v0[i] = acc[ai][bj][m][0][i] * c[i]; v1[i] = acc[ai][bj][m][1][i] * c[4 + i]; }
;                         store8(OUT + (size_t)row * DM + col + bj * 128, v0, v1);
	v_lshlrev_b32_e32 v168, 16, v224
	v_and_b32_e32 v169, 0xffff0000, v224
	v_lshlrev_b32_e32 v170, 16, v225
	v_and_b32_e32 v171, 0xffff0000, v225
	v_lshlrev_b32_e32 v172, 16, v226
	v_and_b32_e32 v173, 0xffff0000, v226
	v_lshlrev_b32_e32 v174, 16, v227
	v_and_b32_e32 v175, 0xffff0000, v227
	v_pk_mul_f32 v[176:177], v[30:31], v[168:169]
	v_pk_mul_f32 v[178:179], v[32:33], v[170:171]
	v_pk_mul_f32 v[180:181], v[26:27], v[172:173]
	v_pk_mul_f32 v[182:183], v[28:29], v[174:175]
	v_cvt_pk_bf16_f32 v176, v176, v177
	v_cvt_pk_bf16_f32 v177, v178, v179
	v_cvt_pk_bf16_f32 v178, v180, v181
	v_cvt_pk_bf16_f32 v179, v182, v183
	global_store_dwordx4 v156, v[176:179], s[18:19] offset:256
	s_nop 1
	s_waitcnt vmcnt(15)
	v_lshlrev_b32_e32 v168, 16, v228
	v_and_b32_e32 v169, 0xffff0000, v228
	v_lshlrev_b32_e32 v170, 16, v229
	v_and_b32_e32 v171, 0xffff0000, v229
	v_lshlrev_b32_e32 v172, 16, v230
	v_and_b32_e32 v173, 0xffff0000, v230
	v_lshlrev_b32_e32 v174, 16, v231
	v_and_b32_e32 v175, 0xffff0000, v231
	v_pk_mul_f32 v[176:177], v[54:55], v[168:169]
	v_pk_mul_f32 v[178:179], v[56:57], v[170:171]
	v_pk_mul_f32 v[180:181], v[50:51], v[172:173]
	v_pk_mul_f32 v[182:183], v[52:53], v[174:175]
	v_cvt_pk_bf16_f32 v176, v176, v177
	v_cvt_pk_bf16_f32 v177, v178, v179
	v_cvt_pk_bf16_f32 v178, v180, v181
	v_cvt_pk_bf16_f32 v179, v182, v183
	global_store_dwordx4 v157, v[176:179], s[18:19]
	s_nop 1
	s_waitcnt vmcnt(15)
	v_lshlrev_b32_e32 v168, 16, v232
	v_and_b32_e32 v169, 0xffff0000, v232
	v_lshlrev_b32_e32 v170, 16, v233
	v_and_b32_e32 v171, 0xffff0000, v233
	v_lshlrev_b32_e32 v172, 16, v234
	v_and_b32_e32 v173, 0xffff0000, v234
	v_lshlrev_b32_e32 v174, 16, v235
	v_and_b32_e32 v175, 0xffff0000, v235
	v_pk_mul_f32 v[176:177], v[22:23], v[168:169]
	v_pk_mul_f32 v[178:179], v[24:25], v[170:171]
	v_pk_mul_f32 v[180:181], v[18:19], v[172:173]
	v_pk_mul_f32 v[182:183], v[20:21], v[174:175]
	v_cvt_pk_bf16_f32 v176, v176, v177
	v_cvt_pk_bf16_f32 v177, v178, v179
	v_cvt_pk_bf16_f32 v178, v180, v181
	v_cvt_pk_bf16_f32 v179, v182, v183
	global_store_dwordx4 v157, v[176:179], s[18:19] offset:256
	s_nop 1
	s_waitcnt vmcnt(15)
	v_lshlrev_b32_e32 v168, 16, v236
	v_and_b32_e32 v169, 0xffff0000, v236
	v_lshlrev_b32_e32 v170, 16, v237
	v_and_b32_e32 v171, 0xffff0000, v237
	v_lshlrev_b32_e32 v172, 16, v238
	v_and_b32_e32 v173, 0xffff0000, v238
	v_lshlrev_b32_e32 v174, 16, v239
	v_and_b32_e32 v175, 0xffff0000, v239
	v_pk_mul_f32 v[176:177], v[46:47], v[168:169]
	v_pk_mul_f32 v[178:179], v[48:49], v[170:171]
	v_pk_mul_f32 v[180:181], v[42:43], v[172:173]
	v_pk_mul_f32 v[182:183], v[44:45], v[174:175]
	v_cvt_pk_bf16_f32 v176, v176, v177
	v_cvt_pk_bf16_f32 v177, v178, v179
	v_cvt_pk_bf16_f32 v178, v180, v181
	v_cvt_pk_bf16_f32 v179, v182, v183
	global_store_dwordx4 v158, v[176:179], s[18:19]
	s_nop 1
	s_waitcnt vmcnt(15)
	v_lshlrev_b32_e32 v168, 16, v240
	v_and_b32_e32 v169, 0xffff0000, v240
	v_lshlrev_b32_e32 v170, 16, v241
	v_and_b32_e32 v171, 0xffff0000, v241
	v_lshlrev_b32_e32 v172, 16, v242
	v_and_b32_e32 v173, 0xffff0000, v242
	v_lshlrev_b32_e32 v174, 16, v243
	v_and_b32_e32 v175, 0xffff0000, v243
	v_pk_mul_f32 v[176:177], v[14:15], v[168:169]
	v_pk_mul_f32 v[178:179], v[16:17], v[170:171]
	v_pk_mul_f32 v[180:181], v[10:11], v[172:173]
	v_pk_mul_f32 v[182:183], v[12:13], v[174:175]
	v_cvt_pk_bf16_f32 v176, v176, v177
	v_cvt_pk_bf16_f32 v177, v178, v179
	v_cvt_pk_bf16_f32 v178, v180, v181
	v_cvt_pk_bf16_f32 v179, v182, v183
	global_store_dwordx4 v158, v[176:179], s[18:19] offset:256
	s_nop 1
	s_waitcnt vmcnt(15)
	v_lshlrev_b32_e32 v168, 16, v244
	v_and_b32_e32 v169, 0xffff0000, v244
	v_lshlrev_b32_e32 v170, 16, v245
	v_and_b32_e32 v171, 0xffff0000, v245
	v_lshlrev_b32_e32 v172, 16, v246
	v_and_b32_e32 v173, 0xffff0000, v246
	v_lshlrev_b32_e32 v174, 16, v247
	v_and_b32_e32 v175, 0xffff0000, v247
	v_pk_mul_f32 v[176:177], v[38:39], v[168:169]
	v_pk_mul_f32 v[178:179], v[40:41], v[170:171]
	v_pk_mul_f32 v[180:181], v[34:35], v[172:173]
	v_pk_mul_f32 v[182:183], v[36:37], v[174:175]
	v_cvt_pk_bf16_f32 v176, v176, v177
	v_cvt_pk_bf16_f32 v177, v178, v179
	v_cvt_pk_bf16_f32 v178, v180, v181
	v_cvt_pk_bf16_f32 v179, v182, v183
	global_store_dwordx4 v159, v[176:179], s[18:19]
	s_nop 1
	s_waitcnt vmcnt(15)
	v_lshlrev_b32_e32 v168, 16, v248
	v_and_b32_e32 v169, 0xffff0000, v248
	v_lshlrev_b32_e32 v170, 16, v249
	v_and_b32_e32 v171, 0xffff0000, v249
	v_lshlrev_b32_e32 v172, 16, v250
	v_and_b32_e32 v173, 0xffff0000, v250
	v_lshlrev_b32_e32 v174, 16, v251
	v_and_b32_e32 v175, 0xffff0000, v251
	v_pk_mul_f32 v[176:177], v[6:7], v[168:169]
	v_pk_mul_f32 v[178:179], v[8:9], v[170:171]
	v_pk_mul_f32 v[180:181], v[2:3], v[172:173]
	v_pk_mul_f32 v[182:183], v[4:5], v[174:175]
	v_cvt_pk_bf16_f32 v176, v176, v177
	v_cvt_pk_bf16_f32 v177, v178, v179
	v_cvt_pk_bf16_f32 v178, v180, v181
	v_cvt_pk_bf16_f32 v179, v182, v183
	global_store_dwordx4 v159, v[176:179], s[18:19] offset:256
	s_nop 1
.Lmrg_done:
.LBB0_1037:
	s_andn2_b64 vcc, exec, s[4:5]
	s_mov_b64 s[4:5], -1
	s_cbranch_vccnz .LBB0_964
	s_branch .LBB0_1040

; DI float bf_lo(unsigned u) { return __uint_as_float(u << 16); }
; DI float bf_hi(unsigned u) { return __uint_as_float(u & 0xffff0000u); }
;     DI void operator()(Acc& acc, const pg8::Unit& u, int wr, int wc, int fr, int fq, const Pre&) const {
;         const int col = u.pn * 256 + wc * 32 + fq * 8;
; #pragma unroll
;         for (int ai = 0; ai < 2; ++ai)
; #pragma unroll
;             for (int m = 0; m < 4; ++m) {
;                 const int row = u.pm * 256 + ai * 128 + wr * 64 + m * 16 + fr;
;                 float ss = 0.f;
; #pragma unroll
;                 for (int bj = 0; bj < 2; ++bj) {
;                     const size_t off = (size_t)row * DM + col + bj * 128;
;                     f32x4 r0, r1;
;                     if (RES_BF16) { const u32x4 rb = *(const u32x4*)(xb + off); r0 = (f32x4){bf_lo(rb.x), bf_hi(rb.x), bf_lo(rb.y), bf_hi(rb.y)}; r1 = (f32x4){bf_lo(rb.z), bf_hi(rb.z), bf_lo(rb.w), bf_hi(rb.w)}; }
;                     else { r0 = *(const f32x4*)(res + off); r1 = *(const f32x4*)(res + off + 4); }
;                     const f32x4 v0 = r0 + acc[ai][bj][m][0] * coef, v1 = r1 + acc[ai][bj][m][1] * coef;
;                     if (WRITE_F32) { *(f32x4*)(out + off) = v0; *(f32x4*)(out + off + 4) = v1; }
;                     if (WRITE_XB) { store8(xb + off, v0, v1);
.LBB0_1334:
	v_lshl_add_u32 v146, s43, 8, v148
	v_lshl_or_b32 v144, s44, 8, v150
	v_lshl_add_u32 v145, v146, 10, v144
	s_and_b64 vcc, exec, s[0:1]
	s_mov_b64 s[0:1], -1
	v_lshlrev_b32_e32 v224, 1, v145
	v_add_u32_e32 v225, 0x8000, v224
	v_add_u32_e32 v226, 0x10000, v224
	v_add_u32_e32 v227, 0x18000, v224
	v_add_u32_e32 v228, 0x40000, v224
	v_add_u32_e32 v229, 0x48000, v224
	v_add_u32_e32 v230, 0x50000, v224
	v_add_u32_e32 v231, 0x58000, v224
	global_load_dwordx4 v[160:163], v224, s[30:31]
	global_load_dwordx4 v[164:167], v224, s[30:31] offset:256
	global_load_dwordx4 v[168:171], v225, s[30:31]
	global_load_dwordx4 v[172:175], v225, s[30:31] offset:256
	global_load_dwordx4 v[176:179], v226, s[30:31]
	global_load_dwordx4 v[180:183], v226, s[30:31] offset:256
	global_load_dwordx4 v[184:187], v227, s[30:31]
	global_load_dwordx4 v[188:191], v227, s[30:31] offset:256
	global_load_dwordx4 v[192:195], v228, s[30:31]
	global_load_dwordx4 v[196:199], v228, s[30:31] offset:256
	global_load_dwordx4 v[200:203], v229, s[30:31]
	global_load_dwordx4 v[204:207], v229, s[30:31] offset:256
	global_load_dwordx4 v[208:211], v230, s[30:31]
	global_load_dwordx4 v[212:215], v230, s[30:31] offset:256
	global_load_dwordx4 v[216:219], v231, s[30:31]
	global_load_dwordx4 v[220:223], v231, s[30:31] offset:256
	v_lshlrev_b32_e32 v232, 1, v224
	v_lshlrev_b32_e32 v233, 1, v225
	v_lshlrev_b32_e32 v234, 1, v226
	v_lshlrev_b32_e32 v235, 1, v227
	v_lshlrev_b32_e32 v236, 1, v228
	v_lshlrev_b32_e32 v237, 1, v229
	v_lshlrev_b32_e32 v238, 1, v230
	v_lshlrev_b32_e32 v239, 1, v231
	s_waitcnt vmcnt(15)
	v_lshlrev_b32_e32 v240, 16, v160
	v_and_b32_e32 v241, 0xffff0000, v160
	v_lshlrev_b32_e32 v242, 16, v161
	v_and_b32_e32 v243, 0xffff0000, v161
	v_lshlrev_b32_e32 v244, 16, v162
	v_and_b32_e32 v245, 0xffff0000, v162
	v_lshlrev_b32_e32 v246, 16, v163
	v_and_b32_e32 v247, 0xffff0000, v163
	v_pk_fma_f32 v[124:125], v[124:125], 0.5, v[240:241] op_sel_hi:[1,0,1]
	v_pk_fma_f32 v[126:127], v[126:127], 0.5, v[242:243] op_sel_hi:[1,0,1]
	v_pk_fma_f32 v[120:121], v[120:121], 0.5, v[244:245] op_sel_hi:[1,0,1]
	v_pk_fma_f32 v[122:123], v[122:123], 0.5, v[246:247] op_sel_hi:[1,0,1]
	global_store_dwordx4 v232, v[124:127], s[6:7]
	global_store_dwordx4 v232, v[120:123], s[6:7] offset:16
	s_waitcnt vmcnt(16)
	v_lshlrev_b32_e32 v240, 16, v164
	v_and_b32_e32 v241, 0xffff0000, v164
	v_lshlrev_b32_e32 v242, 16, v165
	v_and_b32_e32 v243, 0xffff0000, v165
	v_lshlrev_b32_e32 v244, 16, v166
	v_and_b32_e32 v245, 0xffff0000, v166
	v_lshlrev_b32_e32 v246, 16, v167
	v_and_b32_e32 v247, 0xffff0000, v167
	v_pk_fma_f32 v[116:117], v[116:117], 0.5, v[240:241] op_sel_hi:[1,0,1]
	v_pk_fma_f32 v[118:119], v[118:119], 0.5, v[242:243] op_sel_hi:[1,0,1]
	v_pk_fma_f32 v[112:113], v[112:113], 0.5, v[244:245] op_sel_hi:[1,0,1]
	v_pk_fma_f32 v[114:115], v[114:115], 0.5, v[246:247] op_sel_hi:[1,0,1]
	global_store_dwordx4 v232, v[116:119], s[6:7] offset:512
	global_store_dwordx4 v232, v[112:115], s[6:7] offset:528
	s_waitcnt vmcnt(17)
	v_lshlrev_b32_e32 v240, 16, v168
	v_and_b32_e32 v241, 0xffff0000, v168
	v_lshlrev_b32_e32 v242, 16, v169
	v_and_b32_e32 v243, 0xffff0000, v169
	v_lshlrev_b32_e32 v244, 16, v170
	v_and_b32_e32 v245, 0xffff0000, v170
	v_lshlrev_b32_e32 v246, 16, v171
	v_and_b32_e32 v247, 0xffff0000, v171
	v_pk_fma_f32 v[108:109], v[108:109], 0.5, v[240:241] op_sel_hi:[1,0,1]
	v_pk_fma_f32 v[110:111], v[110:111], 0.5, v[242:243] op_sel_hi:[1,0,1]
	v_pk_fma_f32 v[104:105], v[104:105], 0.5, v[244:245] op_sel_hi:[1,0,1]
	v_pk_fma_f32 v[106:107], v[106:107], 0.5, v[246:247] op_sel_hi:[1,0,1]
	global_store_dwordx4 v233, v[108:111], s[6:7]
	global_store_dwordx4 v233, v[104:107], s[6:7] offset:16
	s_waitcnt vmcnt(18)
	v_lshlrev_b32_e32 v240, 16, v172
	v_and_b32_e32 v241, 0xffff0000, v172
	v_lshlrev_b32_e32 v242, 16, v173
	v_and_b32_e32 v243, 0xffff0000, v173
	v_lshlrev_b32_e32 v244, 16, v174
	v_and_b32_e32 v245, 0xffff0000, v174
	v_lshlrev_b32_e32 v246, 16, v175
	v_and_b32_e32 v247, 0xffff0000, v175
	v_pk_fma_f32 v[100:101], v[100:101], 0.5, v[240:241] op_sel_hi:[1,0,1]
	v_pk_fma_f32 v[102:103], v[102:103], 0.5, v[242:243] op_sel_hi:[1,0,1]
	v_pk_fma_f32 v[96:97], v[96:97], 0.5, v[244:245] op_sel_hi:[1,0,1]
	v_pk_fma_f32 v[98:99], v[98:99], 0.5, v[246:247] op_sel_hi:[1,0,1]
	global_store_dwordx4 v233, v[100:103], s[6:7] offset:512
	global_store_dwordx4 v233, v[96:99], s[6:7] offset:528
	s_waitcnt vmcnt(19)
	v_lshlrev_b32_e32 v240, 16, v176
	v_and_b32_e32 v241, 0xffff0000, v176
	v_lshlrev_b32_e32 v242, 16, v177
	v_and_b32_e32 v243, 0xffff0000, v177
	v_lshlrev_b32_e32 v244, 16, v178
	v_and_b32_e32 v245, 0xffff0000, v178
	v_lshlrev_b32_e32 v246, 16, v179
	v_and_b32_e32 v247, 0xffff0000, v179
	v_pk_fma_f32 v[92:93], v[92:93], 0.5, v[240:241] op_sel_hi:[1,0,1]
	v_pk_fma_f32 v[94:95], v[94:95], 0.5, v[242:243] op_sel_hi:[1,0,1]
	v_pk_fma_f32 v[88:89], v[88:89], 0.5, v[244:245] op_sel_hi:[1,0,1]
	v_pk_fma_f32 v[90:91], v[90:91], 0.5, v[246:247] op_sel_hi:[1,0,1]
	global_store_dwordx4 v234, v[92:95], s[6:7]
	global_store_dwordx4 v234, v[88:91], s[6:7] offset:16
	s_waitcnt vmcnt(20)
	v_lshlrev_b32_e32 v240, 16, v180
	v_and_b32_e32 v241, 0xffff0000, v180
	v_lshlrev_b32_e32 v242, 16, v181
	v_and_b32_e32 v243, 0xffff0000, v181
	v_lshlrev_b32_e32 v244, 16, v182
	v_and_b32_e32 v245, 0xffff0000, v182
	v_lshlrev_b32_e32 v246, 16, v183
	v_and_b32_e32 v247, 0xffff0000, v183
	v_pk_fma_f32 v[84:85], v[84:85], 0.5, v[240:241] op_sel_hi:[1,0,1]
	v_pk_fma_f32 v[86:87], v[86:87], 0.5, v[242:243] op_sel_hi:[1,0,1]
	v_pk_fma_f32 v[80:81], v[80:81], 0.5, v[244:245] op_sel_hi:[1,0,1]
	v_pk_fma_f32 v[82:83], v[82:83], 0.5, v[246:247] op_sel_hi:[1,0,1]
	global_store_dwordx4 v234, v[84:87], s[6:7] offset:512
	global_store_dwordx4 v234, v[80:83], s[6:7] offset:528
	s_waitcnt vmcnt(21)
; DI float bf_lo(unsigned u) { return __uint_as_float(u << 16); }
; DI float bf_hi(unsigned u) { return __uint_as_float(u & 0xffff0000u); }
;     DI void operator()(Acc& acc, const pg8::Unit& u, int wr, int wc, int fr, int fq, const Pre&) const {
;         const int col = u.pn * 256 + wc * 32 + fq * 8;
; #pragma unroll
;         for (int ai = 0; ai < 2; ++ai)
; #pragma unroll
;             for (int m = 0; m < 4; ++m) {
;                 const int row = u.pm * 256 + ai * 128 + wr * 64 + m * 16 + fr;
;                 float ss = 0.f;
; #pragma unroll
;                 for (int bj = 0; bj < 2; ++bj) {
;                     const size_t off = (size_t)row * DM + col + bj * 128;
;                     f32x4 r0, r1;
;                     if (RES_BF16) { const u32x4 rb = *(const u32x4*)(xb + off); r0 = (f32x4){bf_lo(rb.x), bf_hi(rb.x), bf_lo(rb.y), bf_hi(rb.y)}; r1 = (f32x4){bf_lo(rb.z), bf_hi(rb.z), bf_lo(rb.w), bf_hi(rb.w)}; }
;                     else { r0 = *(const f32x4*)(res + off); r1 = *(const f32x4*)(res + off + 4); }
;                     const f32x4 v0 = r0 + acc[ai][bj][m][0] * coef, v1 = r1 + acc[ai][bj][m][1] * coef;
;                     if (WRITE_F32) { *(f32x4*)(out + off) = v0; *(f32x4*)(out + off + 4) = v1; }
;                     if (WRITE_XB) { store8(xb + off, v0, v1);
	v_lshlrev_b32_e32 v240, 16, v184
	v_and_b32_e32 v241, 0xffff0000, v184
	v_lshlrev_b32_e32 v242, 16, v185
	v_and_b32_e32 v243, 0xffff0000, v185
	v_lshlrev_b32_e32 v244, 16, v186
	v_and_b32_e32 v245, 0xffff0000, v186
	v_lshlrev_b32_e32 v246, 16, v187
	v_and_b32_e32 v247, 0xffff0000, v187
	v_pk_fma_f32 v[76:77], v[76:77], 0.5, v[240:241] op_sel_hi:[1,0,1]
	v_pk_fma_f32 v[78:79], v[78:79], 0.5, v[242:243] op_sel_hi:[1,0,1]
	v_pk_fma_f32 v[72:73], v[72:73], 0.5, v[244:245] op_sel_hi:[1,0,1]
	v_pk_fma_f32 v[74:75], v[74:75], 0.5, v[246:247] op_sel_hi:[1,0,1]
	global_store_dwordx4 v235, v[76:79], s[6:7]
	global_store_dwordx4 v235, v[72:75], s[6:7] offset:16
	s_waitcnt vmcnt(22)
	v_lshlrev_b32_e32 v240, 16, v188
	v_and_b32_e32 v241, 0xffff0000, v188
	v_lshlrev_b32_e32 v242, 16, v189
	v_and_b32_e32 v243, 0xffff0000, v189
	v_lshlrev_b32_e32 v244, 16, v190
	v_and_b32_e32 v245, 0xffff0000, v190
	v_lshlrev_b32_e32 v246, 16, v191
	v_and_b32_e32 v247, 0xffff0000, v191
	v_pk_fma_f32 v[68:69], v[68:69], 0.5, v[240:241] op_sel_hi:[1,0,1]
	v_pk_fma_f32 v[70:71], v[70:71], 0.5, v[242:243] op_sel_hi:[1,0,1]
	v_pk_fma_f32 v[64:65], v[64:65], 0.5, v[244:245] op_sel_hi:[1,0,1]
	v_pk_fma_f32 v[66:67], v[66:67], 0.5, v[246:247] op_sel_hi:[1,0,1]
	global_store_dwordx4 v235, v[68:71], s[6:7] offset:512
	global_store_dwordx4 v235, v[64:67], s[6:7] offset:528
	s_waitcnt vmcnt(23)
	v_lshlrev_b32_e32 v240, 16, v192
	v_and_b32_e32 v241, 0xffff0000, v192
	v_lshlrev_b32_e32 v242, 16, v193
	v_and_b32_e32 v243, 0xffff0000, v193
	v_lshlrev_b32_e32 v244, 16, v194
	v_and_b32_e32 v245, 0xffff0000, v194
	v_lshlrev_b32_e32 v246, 16, v195
	v_and_b32_e32 v247, 0xffff0000, v195
	v_pk_fma_f32 v[60:61], v[60:61], 0.5, v[240:241] op_sel_hi:[1,0,1]
	v_pk_fma_f32 v[62:63], v[62:63], 0.5, v[242:243] op_sel_hi:[1,0,1]
	v_pk_fma_f32 v[56:57], v[56:57], 0.5, v[244:245] op_sel_hi:[1,0,1]
	v_pk_fma_f32 v[58:59], v[58:59], 0.5, v[246:247] op_sel_hi:[1,0,1]
	global_store_dwordx4 v236, v[60:63], s[6:7]
	global_store_dwordx4 v236, v[56:59], s[6:7] offset:16
	s_waitcnt vmcnt(24)
	v_lshlrev_b32_e32 v240, 16, v196
	v_and_b32_e32 v241, 0xffff0000, v196
	v_lshlrev_b32_e32 v242, 16, v197
	v_and_b32_e32 v243, 0xffff0000, v197
	v_lshlrev_b32_e32 v244, 16, v198
	v_and_b32_e32 v245, 0xffff0000, v198
	v_lshlrev_b32_e32 v246, 16, v199
	v_and_b32_e32 v247, 0xffff0000, v199
	v_pk_fma_f32 v[52:53], v[52:53], 0.5, v[240:241] op_sel_hi:[1,0,1]
	v_pk_fma_f32 v[54:55], v[54:55], 0.5, v[242:243] op_sel_hi:[1,0,1]
	v_pk_fma_f32 v[48:49], v[48:49], 0.5, v[244:245] op_sel_hi:[1,0,1]
	v_pk_fma_f32 v[50:51], v[50:51], 0.5, v[246:247] op_sel_hi:[1,0,1]
	global_store_dwordx4 v236, v[52:55], s[6:7] offset:512
	global_store_dwordx4 v236, v[48:51], s[6:7] offset:528
	s_waitcnt vmcnt(25)
	v_lshlrev_b32_e32 v240, 16, v200
	v_and_b32_e32 v241, 0xffff0000, v200
	v_lshlrev_b32_e32 v242, 16, v201
	v_and_b32_e32 v243, 0xffff0000, v201
	v_lshlrev_b32_e32 v244, 16, v202
	v_and_b32_e32 v245, 0xffff0000, v202
	v_lshlrev_b32_e32 v246, 16, v203
	v_and_b32_e32 v247, 0xffff0000, v203
	v_pk_fma_f32 v[44:45], v[44:45], 0.5, v[240:241] op_sel_hi:[1,0,1]
	v_pk_fma_f32 v[46:47], v[46:47], 0.5, v[242:243] op_sel_hi:[1,0,1]
	v_pk_fma_f32 v[40:41], v[40:41], 0.5, v[244:245] op_sel_hi:[1,0,1]
	v_pk_fma_f32 v[42:43], v[42:43], 0.5, v[246:247] op_sel_hi:[1,0,1]
	global_store_dwordx4 v237, v[44:47], s[6:7]
	global_store_dwordx4 v237, v[40:43], s[6:7] offset:16
	s_waitcnt vmcnt(26)
	v_lshlrev_b32_e32 v240, 16, v204
	v_and_b32_e32 v241, 0xffff0000, v204
	v_lshlrev_b32_e32 v242, 16, v205
	v_and_b32_e32 v243, 0xffff0000, v205
	v_lshlrev_b32_e32 v244, 16, v206
	v_and_b32_e32 v245, 0xffff0000, v206
	v_lshlrev_b32_e32 v246, 16, v207
	v_and_b32_e32 v247, 0xffff0000, v207
	v_pk_fma_f32 v[36:37], v[36:37], 0.5, v[240:241] op_sel_hi:[1,0,1]
	v_pk_fma_f32 v[38:39], v[38:39], 0.5, v[242:243] op_sel_hi:[1,0,1]
	v_pk_fma_f32 v[32:33], v[32:33], 0.5, v[244:245] op_sel_hi:[1,0,1]
	v_pk_fma_f32 v[34:35], v[34:35], 0.5, v[246:247] op_sel_hi:[1,0,1]
	global_store_dwordx4 v237, v[36:39], s[6:7] offset:512
	global_store_dwordx4 v237, v[32:35], s[6:7] offset:528
	s_waitcnt vmcnt(27)
	v_lshlrev_b32_e32 v240, 16, v208
	v_and_b32_e32 v241, 0xffff0000, v208
	v_lshlrev_b32_e32 v242, 16, v209
	v_and_b32_e32 v243, 0xffff0000, v209
	v_lshlrev_b32_e32 v244, 16, v210
	v_and_b32_e32 v245, 0xffff0000, v210
	v_lshlrev_b32_e32 v246, 16, v211
	v_and_b32_e32 v247, 0xffff0000, v211
	v_pk_fma_f32 v[28:29], v[28:29], 0.5, v[240:241] op_sel_hi:[1,0,1]
	v_pk_fma_f32 v[30:31], v[30:31], 0.5, v[242:243] op_sel_hi:[1,0,1]
	v_pk_fma_f32 v[24:25], v[24:25], 0.5, v[244:245] op_sel_hi:[1,0,1]
	v_pk_fma_f32 v[26:27], v[26:27], 0.5, v[246:247] op_sel_hi:[1,0,1]
	global_store_dwordx4 v238, v[28:31], s[6:7]
	global_store_dwordx4 v238, v[24:27], s[6:7] offset:16
	s_waitcnt vmcnt(28)
	v_lshlrev_b32_e32 v240, 16, v212
	v_and_b32_e32 v241, 0xffff0000, v212
	v_lshlrev_b32_e32 v242, 16, v213
	v_and_b32_e32 v243, 0xffff0000, v213
	v_lshlrev_b32_e32 v244, 16, v214
	v_and_b32_e32 v245, 0xffff0000, v214
	v_lshlrev_b32_e32 v246, 16, v215
	v_and_b32_e32 v247, 0xffff0000, v215
	v_pk_fma_f32 v[20:21], v[20:21], 0.5, v[240:241] op_sel_hi:[1,0,1]
	v_pk_fma_f32 v[22:23], v[22:23], 0.5, v[242:243] op_sel_hi:[1,0,1]
	v_pk_fma_f32 v[16:17], v[16:17], 0.5, v[244:245] op_sel_hi:[1,0,1]
	v_pk_fma_f32 v[18:19], v[18:19], 0.5, v[246:247] op_sel_hi:[1,0,1]
	global_store_dwordx4 v238, v[20:23], s[6:7] offset:512
	global_store_dwordx4 v238, v[16:19], s[6:7] offset:528
	s_waitcnt vmcnt(29)
	v_lshlrev_b32_e32 v240, 16, v216
	v_and_b32_e32 v241, 0xffff0000, v216
	v_lshlrev_b32_e32 v242, 16, v217
	v_and_b32_e32 v243, 0xffff0000, v217
	v_lshlrev_b32_e32 v244, 16, v218
	v_and_b32_e32 v245, 0xffff0000, v218
	v_lshlrev_b32_e32 v246, 16, v219
	v_and_b32_e32 v247, 0xffff0000, v219
	v_pk_fma_f32 v[12:13], v[12:13], 0.5, v[240:241] op_sel_hi:[1,0,1]
	v_pk_fma_f32 v[14:15], v[14:15], 0.5, v[242:243] op_sel_hi:[1,0,1]
	v_pk_fma_f32 v[8:9], v[8:9], 0.5, v[244:245] op_sel_hi:[1,0,1]
	v_pk_fma_f32 v[10:11], v[10:11], 0.5, v[246:247] op_sel_hi:[1,0,1]
	global_store_dwordx4 v239, v[12:15], s[6:7]
	global_store_dwordx4 v239, v[8:11], s[6:7] offset:16
	s_waitcnt vmcnt(30)
	v_lshlrev_b32_e32 v240, 16, v220
	v_and_b32_e32 v241, 0xffff0000, v220
	v_lshlrev_b32_e32 v242, 16, v221
	v_and_b32_e32 v243, 0xffff0000, v221
	v_lshlrev_b32_e32 v244, 16, v222
	v_and_b32_e32 v245, 0xffff0000, v222
	v_lshlrev_b32_e32 v246, 16, v223
	v_and_b32_e32 v247, 0xffff0000, v223
	v_pk_fma_f32 v[4:5], v[4:5], 0.5, v[240:241] op_sel_hi:[1,0,1]
	v_pk_fma_f32 v[6:7], v[6:7], 0.5, v[242:243] op_sel_hi:[1,0,1]
	v_pk_fma_f32 v[0:1], v[0:1], 0.5, v[244:245] op_sel_hi:[1,0,1]
	v_pk_fma_f32 v[2:3], v[2:3], 0.5, v[246:247] op_sel_hi:[1,0,1]
	global_store_dwordx4 v239, v[4:7], s[6:7] offset:512
	global_store_dwordx4 v239, v[0:3], s[6:7] offset:528
	s_cbranch_vccnz .LBB0_1319
	s_andn2_b64 vcc, exec, s[8:9]
	s_cbranch_vccnz .LBB0_1318
	s_barrier
	s_branch .LBB0_1318
